# GEMM unit header: the redundant first accumulator-zeroing block (128 v_mov per tile) moved out of line onto the never-taken K-loop-skip path
# speedup vs baseline: 1.0123x; 1.0107x over previous
.LBB0_38:
	s_andn2_b64 vcc, exec, s[46:47]
	s_cbranch_vccnz .Lzskip_0
	s_add_u32 s20, s20, 0x80
	s_addc_u32 s21, s21, 0
	s_add_u32 vcc_lo, s80, 0x100
	v_mov_b32_e32 v2, 0
	s_addc_u32 vcc_hi, s81, 0
	s_mov_b32 s80, 0
	v_mov_b32_e32 v3, v2
	v_mov_b32_e32 v4, v2
	v_mov_b32_e32 v5, v2
	v_mov_b32_e32 v6, v2
	v_mov_b32_e32 v7, v2
	v_mov_b32_e32 v8, v2
	v_mov_b32_e32 v9, v2
	v_mov_b32_e32 v18, v2
	v_mov_b32_e32 v19, v2
	v_mov_b32_e32 v20, v2
	v_mov_b32_e32 v21, v2
	v_mov_b32_e32 v22, v2
	v_mov_b32_e32 v23, v2
	v_mov_b32_e32 v24, v2
	v_mov_b32_e32 v25, v2
	v_mov_b32_e32 v34, v2
	v_mov_b32_e32 v35, v2
	v_mov_b32_e32 v36, v2
	v_mov_b32_e32 v37, v2
	v_mov_b32_e32 v38, v2
	v_mov_b32_e32 v39, v2
	v_mov_b32_e32 v40, v2
	v_mov_b32_e32 v41, v2
	v_mov_b32_e32 v50, v2
	v_mov_b32_e32 v51, v2
	v_mov_b32_e32 v52, v2
	v_mov_b32_e32 v53, v2
	v_mov_b32_e32 v54, v2
	v_mov_b32_e32 v55, v2
	v_mov_b32_e32 v56, v2
	v_mov_b32_e32 v57, v2
	v_mov_b32_e32 v10, v2
	v_mov_b32_e32 v11, v2
	v_mov_b32_e32 v12, v2
	v_mov_b32_e32 v13, v2
	v_mov_b32_e32 v14, v2
	v_mov_b32_e32 v15, v2
	v_mov_b32_e32 v16, v2
	v_mov_b32_e32 v17, v2
	v_mov_b32_e32 v26, v2
	v_mov_b32_e32 v27, v2
	v_mov_b32_e32 v28, v2
	v_mov_b32_e32 v29, v2
	v_mov_b32_e32 v30, v2
	v_mov_b32_e32 v31, v2
	v_mov_b32_e32 v32, v2
	v_mov_b32_e32 v33, v2
	v_mov_b32_e32 v42, v2
	v_mov_b32_e32 v43, v2
	v_mov_b32_e32 v44, v2
	v_mov_b32_e32 v45, v2
	v_mov_b32_e32 v46, v2
	v_mov_b32_e32 v47, v2
	v_mov_b32_e32 v48, v2
	v_mov_b32_e32 v49, v2
	v_mov_b32_e32 v58, v2
	v_mov_b32_e32 v59, v2
	v_mov_b32_e32 v60, v2
	v_mov_b32_e32 v61, v2
	v_mov_b32_e32 v62, v2
	v_mov_b32_e32 v63, v2
	v_mov_b32_e32 v64, v2
	v_mov_b32_e32 v65, v2
	v_mov_b32_e32 v66, v2
	v_mov_b32_e32 v67, v2
	v_mov_b32_e32 v68, v2
	v_mov_b32_e32 v69, v2
	v_mov_b32_e32 v70, v2
	v_mov_b32_e32 v71, v2
	v_mov_b32_e32 v72, v2
	v_mov_b32_e32 v73, v2
	v_mov_b32_e32 v82, v2
	v_mov_b32_e32 v83, v2
	v_mov_b32_e32 v84, v2
	v_mov_b32_e32 v85, v2
	v_mov_b32_e32 v86, v2
	v_mov_b32_e32 v87, v2
	v_mov_b32_e32 v88, v2
	v_mov_b32_e32 v89, v2
	v_mov_b32_e32 v102, v2
	v_mov_b32_e32 v103, v2
	v_mov_b32_e32 v104, v2
	v_mov_b32_e32 v105, v2
	v_mov_b32_e32 v106, v2
	v_mov_b32_e32 v107, v2
	v_mov_b32_e32 v108, v2
	v_mov_b32_e32 v109, v2
	v_mov_b32_e32 v126, v2
	v_mov_b32_e32 v127, v2
	v_mov_b32_e32 v128, v2
	v_mov_b32_e32 v129, v2
	v_mov_b32_e32 v134, v2
	v_mov_b32_e32 v135, v2
	v_mov_b32_e32 v136, v2
	v_mov_b32_e32 v137, v2
	v_mov_b32_e32 v74, v2
	v_mov_b32_e32 v75, v2
	v_mov_b32_e32 v76, v2
	v_mov_b32_e32 v77, v2
	v_mov_b32_e32 v78, v2
	v_mov_b32_e32 v79, v2
	v_mov_b32_e32 v80, v2
	v_mov_b32_e32 v81, v2
	v_mov_b32_e32 v90, v2
	v_mov_b32_e32 v91, v2
	v_mov_b32_e32 v92, v2
	v_mov_b32_e32 v93, v2
	v_mov_b32_e32 v94, v2
	v_mov_b32_e32 v95, v2
	v_mov_b32_e32 v96, v2
	v_mov_b32_e32 v97, v2
	v_mov_b32_e32 v110, v2
	v_mov_b32_e32 v111, v2
	v_mov_b32_e32 v112, v2
	v_mov_b32_e32 v113, v2
	v_mov_b32_e32 v118, v2
	v_mov_b32_e32 v119, v2
	v_mov_b32_e32 v120, v2
	v_mov_b32_e32 v121, v2
	v_mov_b32_e32 v138, v2
	v_mov_b32_e32 v139, v2
	v_mov_b32_e32 v140, v2
	v_mov_b32_e32 v141, v2
	v_mov_b32_e32 v142, v2
	v_mov_b32_e32 v143, v2
	v_mov_b32_e32 v144, v2
	v_mov_b32_e32 v145, v2

.LBB0_65:
	s_andn2_b64 vcc, exec, s[34:35]
	s_cbranch_vccnz .Lzskip_1
	s_add_u32 s20, s20, 0x80
	s_addc_u32 s21, s21, 0
	s_add_u32 vcc_lo, s80, 0x100
	v_mov_b32_e32 v2, 0
	s_addc_u32 vcc_hi, s81, 0
	s_mov_b32 s80, 0
	v_mov_b32_e32 v3, v2
	v_mov_b32_e32 v4, v2
	v_mov_b32_e32 v5, v2
	v_mov_b32_e32 v6, v2
	v_mov_b32_e32 v7, v2
	v_mov_b32_e32 v8, v2
	v_mov_b32_e32 v9, v2
	v_mov_b32_e32 v18, v2
	v_mov_b32_e32 v19, v2
	v_mov_b32_e32 v20, v2
	v_mov_b32_e32 v21, v2
	v_mov_b32_e32 v22, v2
	v_mov_b32_e32 v23, v2
	v_mov_b32_e32 v24, v2
	v_mov_b32_e32 v25, v2
	v_mov_b32_e32 v34, v2
	v_mov_b32_e32 v35, v2
	v_mov_b32_e32 v36, v2
	v_mov_b32_e32 v37, v2
	v_mov_b32_e32 v38, v2
	v_mov_b32_e32 v39, v2
	v_mov_b32_e32 v40, v2
	v_mov_b32_e32 v41, v2
	v_mov_b32_e32 v50, v2
	v_mov_b32_e32 v51, v2
	v_mov_b32_e32 v52, v2
	v_mov_b32_e32 v53, v2
	v_mov_b32_e32 v54, v2
	v_mov_b32_e32 v55, v2
	v_mov_b32_e32 v56, v2
	v_mov_b32_e32 v57, v2
	v_mov_b32_e32 v10, v2
	v_mov_b32_e32 v11, v2
	v_mov_b32_e32 v12, v2
	v_mov_b32_e32 v13, v2
	v_mov_b32_e32 v14, v2
	v_mov_b32_e32 v15, v2
	v_mov_b32_e32 v16, v2
	v_mov_b32_e32 v17, v2
	v_mov_b32_e32 v26, v2
	v_mov_b32_e32 v27, v2
	v_mov_b32_e32 v28, v2
	v_mov_b32_e32 v29, v2
	v_mov_b32_e32 v30, v2
	v_mov_b32_e32 v31, v2
	v_mov_b32_e32 v32, v2
	v_mov_b32_e32 v33, v2
	v_mov_b32_e32 v42, v2
	v_mov_b32_e32 v43, v2
	v_mov_b32_e32 v44, v2
	v_mov_b32_e32 v45, v2
	v_mov_b32_e32 v46, v2
	v_mov_b32_e32 v47, v2
	v_mov_b32_e32 v48, v2
	v_mov_b32_e32 v49, v2
	v_mov_b32_e32 v58, v2
	v_mov_b32_e32 v59, v2
	v_mov_b32_e32 v60, v2
	v_mov_b32_e32 v61, v2
	v_mov_b32_e32 v62, v2
	v_mov_b32_e32 v63, v2
	v_mov_b32_e32 v64, v2
	v_mov_b32_e32 v65, v2
	v_mov_b32_e32 v66, v2
	v_mov_b32_e32 v67, v2
	v_mov_b32_e32 v68, v2
	v_mov_b32_e32 v69, v2
	v_mov_b32_e32 v70, v2
	v_mov_b32_e32 v71, v2
	v_mov_b32_e32 v72, v2
	v_mov_b32_e32 v73, v2
	v_mov_b32_e32 v82, v2
	v_mov_b32_e32 v83, v2
	v_mov_b32_e32 v84, v2
	v_mov_b32_e32 v85, v2
	v_mov_b32_e32 v86, v2
	v_mov_b32_e32 v87, v2
	v_mov_b32_e32 v88, v2
	v_mov_b32_e32 v89, v2
	v_mov_b32_e32 v98, v2
	v_mov_b32_e32 v99, v2
	v_mov_b32_e32 v100, v2
	v_mov_b32_e32 v101, v2
	v_mov_b32_e32 v102, v2
	v_mov_b32_e32 v103, v2
	v_mov_b32_e32 v104, v2
	v_mov_b32_e32 v105, v2
	v_mov_b32_e32 v114, v2
	v_mov_b32_e32 v115, v2
	v_mov_b32_e32 v116, v2
	v_mov_b32_e32 v117, v2
	v_mov_b32_e32 v118, v2
	v_mov_b32_e32 v119, v2
	v_mov_b32_e32 v120, v2
	v_mov_b32_e32 v121, v2
	v_mov_b32_e32 v74, v2
	v_mov_b32_e32 v75, v2
	v_mov_b32_e32 v76, v2
	v_mov_b32_e32 v77, v2
	v_mov_b32_e32 v78, v2
	v_mov_b32_e32 v79, v2
	v_mov_b32_e32 v80, v2
	v_mov_b32_e32 v81, v2
	v_mov_b32_e32 v90, v2
	v_mov_b32_e32 v91, v2
	v_mov_b32_e32 v92, v2
	v_mov_b32_e32 v93, v2
	v_mov_b32_e32 v94, v2
	v_mov_b32_e32 v95, v2
	v_mov_b32_e32 v96, v2
	v_mov_b32_e32 v97, v2
	v_mov_b32_e32 v106, v2
	v_mov_b32_e32 v107, v2
	v_mov_b32_e32 v108, v2
	v_mov_b32_e32 v109, v2
	v_mov_b32_e32 v110, v2
	v_mov_b32_e32 v111, v2
	v_mov_b32_e32 v112, v2
	v_mov_b32_e32 v113, v2
	v_mov_b32_e32 v126, v2
	v_mov_b32_e32 v127, v2
	v_mov_b32_e32 v128, v2
	v_mov_b32_e32 v129, v2
	v_mov_b32_e32 v122, v2
	v_mov_b32_e32 v123, v2
	v_mov_b32_e32 v124, v2
	v_mov_b32_e32 v125, v2

.LBB0_100:
	s_andn2_b64 vcc, exec, s[34:35]
	s_cbranch_vccnz .Lzskip_2
	s_add_u32 s20, s20, 0x80
	s_addc_u32 s21, s21, 0
	s_add_u32 s13, s80, 0x100
	v_mov_b32_e32 v2, 0
	s_addc_u32 vcc_lo, s81, 0
	s_mov_b32 s80, 0
	v_mov_b32_e32 v3, v2
	v_mov_b32_e32 v4, v2
	v_mov_b32_e32 v5, v2
	v_mov_b32_e32 v6, v2
	v_mov_b32_e32 v7, v2
	v_mov_b32_e32 v8, v2
	v_mov_b32_e32 v9, v2
	v_mov_b32_e32 v18, v2
	v_mov_b32_e32 v19, v2
	v_mov_b32_e32 v20, v2
	v_mov_b32_e32 v21, v2
	v_mov_b32_e32 v22, v2
	v_mov_b32_e32 v23, v2
	v_mov_b32_e32 v24, v2
	v_mov_b32_e32 v25, v2
	v_mov_b32_e32 v34, v2
	v_mov_b32_e32 v35, v2
	v_mov_b32_e32 v36, v2
	v_mov_b32_e32 v37, v2
	v_mov_b32_e32 v38, v2
	v_mov_b32_e32 v39, v2
	v_mov_b32_e32 v40, v2
	v_mov_b32_e32 v41, v2
	v_mov_b32_e32 v50, v2
	v_mov_b32_e32 v51, v2
	v_mov_b32_e32 v52, v2
	v_mov_b32_e32 v53, v2
	v_mov_b32_e32 v54, v2
	v_mov_b32_e32 v55, v2
	v_mov_b32_e32 v56, v2
	v_mov_b32_e32 v57, v2
	v_mov_b32_e32 v10, v2
	v_mov_b32_e32 v11, v2
	v_mov_b32_e32 v12, v2
	v_mov_b32_e32 v13, v2
	v_mov_b32_e32 v14, v2
	v_mov_b32_e32 v15, v2
	v_mov_b32_e32 v16, v2
	v_mov_b32_e32 v17, v2
	v_mov_b32_e32 v26, v2
	v_mov_b32_e32 v27, v2
	v_mov_b32_e32 v28, v2
	v_mov_b32_e32 v29, v2
	v_mov_b32_e32 v30, v2
	v_mov_b32_e32 v31, v2
	v_mov_b32_e32 v32, v2
	v_mov_b32_e32 v33, v2
	v_mov_b32_e32 v42, v2
	v_mov_b32_e32 v43, v2
	v_mov_b32_e32 v44, v2
	v_mov_b32_e32 v45, v2
	v_mov_b32_e32 v46, v2
	v_mov_b32_e32 v47, v2
	v_mov_b32_e32 v48, v2
	v_mov_b32_e32 v49, v2
	v_mov_b32_e32 v58, v2
	v_mov_b32_e32 v59, v2
	v_mov_b32_e32 v60, v2
	v_mov_b32_e32 v61, v2
	v_mov_b32_e32 v62, v2
	v_mov_b32_e32 v63, v2
	v_mov_b32_e32 v64, v2
	v_mov_b32_e32 v65, v2
	v_mov_b32_e32 v66, v2
	v_mov_b32_e32 v67, v2
	v_mov_b32_e32 v68, v2
	v_mov_b32_e32 v69, v2
	v_mov_b32_e32 v70, v2
	v_mov_b32_e32 v71, v2
	v_mov_b32_e32 v72, v2
	v_mov_b32_e32 v73, v2
	v_mov_b32_e32 v82, v2
	v_mov_b32_e32 v83, v2
	v_mov_b32_e32 v84, v2
	v_mov_b32_e32 v85, v2
	v_mov_b32_e32 v86, v2
	v_mov_b32_e32 v87, v2
	v_mov_b32_e32 v88, v2
	v_mov_b32_e32 v89, v2
	v_mov_b32_e32 v98, v2
	v_mov_b32_e32 v99, v2
	v_mov_b32_e32 v100, v2
	v_mov_b32_e32 v101, v2
	v_mov_b32_e32 v102, v2
	v_mov_b32_e32 v103, v2
	v_mov_b32_e32 v104, v2
	v_mov_b32_e32 v105, v2
	v_mov_b32_e32 v114, v2
	v_mov_b32_e32 v115, v2
	v_mov_b32_e32 v116, v2
	v_mov_b32_e32 v117, v2
	v_mov_b32_e32 v118, v2
	v_mov_b32_e32 v119, v2
	v_mov_b32_e32 v120, v2
	v_mov_b32_e32 v121, v2
	v_mov_b32_e32 v74, v2
	v_mov_b32_e32 v75, v2
	v_mov_b32_e32 v76, v2
	v_mov_b32_e32 v77, v2
	v_mov_b32_e32 v78, v2
	v_mov_b32_e32 v79, v2
	v_mov_b32_e32 v80, v2
	v_mov_b32_e32 v81, v2
	v_mov_b32_e32 v90, v2
	v_mov_b32_e32 v91, v2
	v_mov_b32_e32 v92, v2
	v_mov_b32_e32 v93, v2
	v_mov_b32_e32 v94, v2
	v_mov_b32_e32 v95, v2
	v_mov_b32_e32 v96, v2
	v_mov_b32_e32 v97, v2
	v_mov_b32_e32 v106, v2
	v_mov_b32_e32 v107, v2
	v_mov_b32_e32 v108, v2
	v_mov_b32_e32 v109, v2
	v_mov_b32_e32 v110, v2
	v_mov_b32_e32 v111, v2
	v_mov_b32_e32 v112, v2
	v_mov_b32_e32 v113, v2
	v_mov_b32_e32 v122, v2
	v_mov_b32_e32 v123, v2
	v_mov_b32_e32 v124, v2
	v_mov_b32_e32 v125, v2
	v_mov_b32_e32 v126, v2
	v_mov_b32_e32 v127, v2
	v_mov_b32_e32 v128, v2
	v_mov_b32_e32 v129, v2

.LBB0_129:
	v_readlane_b32 s20, v252, 38
	v_readlane_b32 s21, v252, 39
	s_andn2_b64 vcc, exec, s[20:21]
	s_cbranch_vccnz .Lzskip_3
	s_lshl_b32 vcc_lo, s98, 8
	s_lshl_b32 s20, s97, 8
	s_or_b32 s99, s20, s83
	s_add_i32 vcc_lo, vcc_lo, s82
	s_add_u32 vcc_hi, s12, 0x100
	s_addc_u32 s42, s13, 0
	s_add_u32 s12, s0, 0x80
	v_mov_b32_e32 v2, v0
	v_mov_b32_e32 v3, v0
	s_addc_u32 s13, s1, 0
	v_mov_b32_e32 v1, v0
	v_mov_b64_e32 v[6:7], v[2:3]
	v_mov_b64_e32 v[10:11], v[2:3]
	v_mov_b64_e32 v[22:23], v[2:3]
	v_mov_b64_e32 v[26:27], v[2:3]
	v_mov_b64_e32 v[38:39], v[2:3]
	v_mov_b64_e32 v[42:43], v[2:3]
	v_mov_b64_e32 v[54:55], v[2:3]
	v_mov_b64_e32 v[58:59], v[2:3]
	v_mov_b64_e32 v[14:15], v[2:3]
	v_mov_b64_e32 v[18:19], v[2:3]
	v_mov_b64_e32 v[30:31], v[2:3]
	v_mov_b64_e32 v[34:35], v[2:3]
	v_mov_b64_e32 v[46:47], v[2:3]
	v_mov_b64_e32 v[50:51], v[2:3]
	v_mov_b64_e32 v[62:63], v[2:3]
	v_mov_b64_e32 v[66:67], v[2:3]
	v_mov_b64_e32 v[70:71], v[2:3]
	v_mov_b64_e32 v[74:75], v[2:3]
	v_mov_b64_e32 v[86:87], v[2:3]
	v_mov_b64_e32 v[90:91], v[2:3]
	v_mov_b64_e32 v[102:103], v[2:3]
	v_mov_b64_e32 v[106:107], v[2:3]
	v_mov_b64_e32 v[122:123], v[2:3]
	v_mov_b64_e32 v[118:119], v[2:3]
	v_mov_b64_e32 v[78:79], v[2:3]
	v_mov_b64_e32 v[82:83], v[2:3]
	v_mov_b64_e32 v[94:95], v[2:3]
	v_mov_b64_e32 v[98:99], v[2:3]
	v_mov_b64_e32 v[114:115], v[2:3]
	v_mov_b64_e32 v[110:111], v[2:3]
	v_mov_b64_e32 v[130:131], v[2:3]
	v_mov_b64_e32 v[126:127], v[2:3]
	v_lshl_add_u64 v[152:153], s[12:13], 0, v[178:179]
	v_lshl_add_u64 v[154:155], s[12:13], 0, v[180:181]
	s_mov_b32 s20, 0
	s_mov_b64 s[12:13], 0
	v_mov_b64_e32 v[4:5], v[0:1]
	v_mov_b64_e32 v[8:9], v[0:1]
	v_mov_b64_e32 v[20:21], v[0:1]
	v_mov_b64_e32 v[24:25], v[0:1]
	v_mov_b64_e32 v[36:37], v[0:1]
	v_mov_b64_e32 v[40:41], v[0:1]
	v_mov_b64_e32 v[52:53], v[0:1]
	v_mov_b64_e32 v[56:57], v[0:1]
	v_mov_b64_e32 v[12:13], v[0:1]
	v_mov_b64_e32 v[16:17], v[0:1]
	v_mov_b64_e32 v[28:29], v[0:1]
	v_mov_b64_e32 v[32:33], v[0:1]
	v_mov_b64_e32 v[44:45], v[0:1]
	v_mov_b64_e32 v[48:49], v[0:1]
	v_mov_b64_e32 v[60:61], v[0:1]
	v_mov_b64_e32 v[64:65], v[0:1]
	v_mov_b64_e32 v[68:69], v[0:1]
	v_mov_b64_e32 v[72:73], v[0:1]
	v_mov_b64_e32 v[84:85], v[0:1]
	v_mov_b64_e32 v[88:89], v[0:1]
	v_mov_b64_e32 v[100:101], v[0:1]
	v_mov_b64_e32 v[104:105], v[0:1]
	v_mov_b64_e32 v[120:121], v[0:1]
	v_mov_b64_e32 v[116:117], v[0:1]
	v_mov_b64_e32 v[76:77], v[0:1]
	v_mov_b64_e32 v[80:81], v[0:1]
	v_mov_b64_e32 v[92:93], v[0:1]
	v_mov_b64_e32 v[96:97], v[0:1]
	v_mov_b64_e32 v[112:113], v[0:1]
	v_mov_b64_e32 v[108:109], v[0:1]
	v_mov_b64_e32 v[128:129], v[0:1]
	v_mov_b64_e32 v[124:125], v[0:1]
	s_cmp_lg_u32 s20, 8
	s_cbranch_scc1 .LBB0_133
	s_branch .LBB0_132

.LBB0_266:
	s_waitcnt vmcnt(0)
	s_andn2_b64 vcc, exec, s[48:49]
	s_cbranch_vccnz .Lzskip_4
	s_add_u32 s0, s0, 0x80
	s_addc_u32 s1, s1, 0
	s_add_u32 s4, s12, 0x100
	v_mov_b32_e32 v2, 0
	s_addc_u32 s20, s13, 0
	s_mov_b32 s12, 0
	v_mov_b32_e32 v3, v2
	v_mov_b32_e32 v4, v2
	v_mov_b32_e32 v5, v2
	v_mov_b32_e32 v6, v2
	v_mov_b32_e32 v7, v2
	v_mov_b32_e32 v8, v2
	v_mov_b32_e32 v9, v2
	v_mov_b32_e32 v18, v2
	v_mov_b32_e32 v19, v2
	v_mov_b32_e32 v20, v2
	v_mov_b32_e32 v21, v2
	v_mov_b32_e32 v22, v2
	v_mov_b32_e32 v23, v2
	v_mov_b32_e32 v24, v2
	v_mov_b32_e32 v25, v2
	v_mov_b32_e32 v34, v2
	v_mov_b32_e32 v35, v2
	v_mov_b32_e32 v36, v2
	v_mov_b32_e32 v37, v2
	v_mov_b32_e32 v38, v2
	v_mov_b32_e32 v39, v2
	v_mov_b32_e32 v40, v2
	v_mov_b32_e32 v41, v2
	v_mov_b32_e32 v50, v2
	v_mov_b32_e32 v51, v2
	v_mov_b32_e32 v52, v2
	v_mov_b32_e32 v53, v2
	v_mov_b32_e32 v54, v2
	v_mov_b32_e32 v55, v2
	v_mov_b32_e32 v56, v2
	v_mov_b32_e32 v57, v2
	v_mov_b32_e32 v10, v2
	v_mov_b32_e32 v11, v2
	v_mov_b32_e32 v12, v2
	v_mov_b32_e32 v13, v2
	v_mov_b32_e32 v14, v2
	v_mov_b32_e32 v15, v2
	v_mov_b32_e32 v16, v2
	v_mov_b32_e32 v17, v2
	v_mov_b32_e32 v26, v2
	v_mov_b32_e32 v27, v2
	v_mov_b32_e32 v28, v2
	v_mov_b32_e32 v29, v2
	v_mov_b32_e32 v30, v2
	v_mov_b32_e32 v31, v2
	v_mov_b32_e32 v32, v2
	v_mov_b32_e32 v33, v2
	v_mov_b32_e32 v42, v2
	v_mov_b32_e32 v43, v2
	v_mov_b32_e32 v44, v2
	v_mov_b32_e32 v45, v2
	v_mov_b32_e32 v46, v2
	v_mov_b32_e32 v47, v2
	v_mov_b32_e32 v48, v2
	v_mov_b32_e32 v49, v2
	v_mov_b32_e32 v58, v2
	v_mov_b32_e32 v59, v2
	v_mov_b32_e32 v60, v2
	v_mov_b32_e32 v61, v2
	v_mov_b32_e32 v62, v2
	v_mov_b32_e32 v63, v2
	v_mov_b32_e32 v64, v2
	v_mov_b32_e32 v65, v2
	v_mov_b32_e32 v66, v2
	v_mov_b32_e32 v67, v2
	v_mov_b32_e32 v68, v2
	v_mov_b32_e32 v69, v2
	v_mov_b32_e32 v70, v2
	v_mov_b32_e32 v71, v2
	v_mov_b32_e32 v72, v2
	v_mov_b32_e32 v73, v2
	v_mov_b32_e32 v82, v2
	v_mov_b32_e32 v83, v2
	v_mov_b32_e32 v84, v2
	v_mov_b32_e32 v85, v2
	v_mov_b32_e32 v86, v2
	v_mov_b32_e32 v87, v2
	v_mov_b32_e32 v88, v2
	v_mov_b32_e32 v89, v2
	v_mov_b32_e32 v98, v2
	v_mov_b32_e32 v99, v2
	v_mov_b32_e32 v100, v2
	v_mov_b32_e32 v101, v2
	v_mov_b32_e32 v102, v2
	v_mov_b32_e32 v103, v2
	v_mov_b32_e32 v104, v2
	v_mov_b32_e32 v105, v2
	v_mov_b32_e32 v114, v2
	v_mov_b32_e32 v115, v2
	v_mov_b32_e32 v116, v2
	v_mov_b32_e32 v117, v2
	v_mov_b32_e32 v118, v2
	v_mov_b32_e32 v119, v2
	v_mov_b32_e32 v120, v2
	v_mov_b32_e32 v121, v2
	v_mov_b32_e32 v74, v2
	v_mov_b32_e32 v75, v2
	v_mov_b32_e32 v76, v2
	v_mov_b32_e32 v77, v2
	v_mov_b32_e32 v78, v2
	v_mov_b32_e32 v79, v2
	v_mov_b32_e32 v80, v2
	v_mov_b32_e32 v81, v2
	v_mov_b32_e32 v90, v2
	v_mov_b32_e32 v91, v2
	v_mov_b32_e32 v92, v2
	v_mov_b32_e32 v93, v2
	v_mov_b32_e32 v94, v2
	v_mov_b32_e32 v95, v2
	v_mov_b32_e32 v96, v2
	v_mov_b32_e32 v97, v2
	v_mov_b32_e32 v106, v2
	v_mov_b32_e32 v107, v2
	v_mov_b32_e32 v108, v2
	v_mov_b32_e32 v109, v2
	v_mov_b32_e32 v110, v2
	v_mov_b32_e32 v111, v2
	v_mov_b32_e32 v112, v2
	v_mov_b32_e32 v113, v2
	v_mov_b32_e32 v122, v2
	v_mov_b32_e32 v123, v2
	v_mov_b32_e32 v124, v2
	v_mov_b32_e32 v125, v2
	v_mov_b32_e32 v126, v2
	v_mov_b32_e32 v127, v2
	v_mov_b32_e32 v128, v2
	v_mov_b32_e32 v129, v2

.Lzskip_0:
	v_mov_b32_e32 v145, 0
	v_mov_b32_e32 v144, v145
	v_mov_b32_e32 v143, v145
	v_mov_b32_e32 v142, v145
	v_mov_b32_e32 v141, v145
	v_mov_b32_e32 v140, v145
	v_mov_b32_e32 v139, v145
	v_mov_b32_e32 v138, v145
	v_mov_b32_e32 v121, v145
	v_mov_b32_e32 v120, v145
	v_mov_b32_e32 v119, v145
	v_mov_b32_e32 v118, v145
	v_mov_b32_e32 v113, v145
	v_mov_b32_e32 v112, v145
	v_mov_b32_e32 v111, v145
	v_mov_b32_e32 v110, v145
	v_mov_b32_e32 v97, v145
	v_mov_b32_e32 v96, v145
	v_mov_b32_e32 v95, v145
	v_mov_b32_e32 v94, v145
	v_mov_b32_e32 v93, v145
	v_mov_b32_e32 v92, v145
	v_mov_b32_e32 v91, v145
	v_mov_b32_e32 v90, v145
	v_mov_b32_e32 v81, v145
	v_mov_b32_e32 v80, v145
	v_mov_b32_e32 v79, v145
	v_mov_b32_e32 v78, v145
	v_mov_b32_e32 v77, v145
	v_mov_b32_e32 v76, v145
	v_mov_b32_e32 v75, v145
	v_mov_b32_e32 v74, v145
	v_mov_b32_e32 v137, v145
	v_mov_b32_e32 v136, v145
	v_mov_b32_e32 v135, v145
	v_mov_b32_e32 v134, v145
	v_mov_b32_e32 v129, v145
	v_mov_b32_e32 v128, v145
	v_mov_b32_e32 v127, v145
	v_mov_b32_e32 v126, v145
	v_mov_b32_e32 v109, v145
	v_mov_b32_e32 v108, v145
	v_mov_b32_e32 v107, v145
	v_mov_b32_e32 v106, v145
	v_mov_b32_e32 v105, v145
	v_mov_b32_e32 v104, v145
	v_mov_b32_e32 v103, v145
	v_mov_b32_e32 v102, v145
	v_mov_b32_e32 v89, v145
	v_mov_b32_e32 v88, v145
	v_mov_b32_e32 v87, v145
	v_mov_b32_e32 v86, v145
	v_mov_b32_e32 v85, v145
	v_mov_b32_e32 v84, v145
	v_mov_b32_e32 v83, v145
	v_mov_b32_e32 v82, v145
	v_mov_b32_e32 v73, v145
	v_mov_b32_e32 v72, v145
	v_mov_b32_e32 v71, v145
	v_mov_b32_e32 v70, v145
	v_mov_b32_e32 v69, v145
	v_mov_b32_e32 v68, v145
	v_mov_b32_e32 v67, v145
	v_mov_b32_e32 v66, v145
	v_mov_b32_e32 v65, v145
	v_mov_b32_e32 v64, v145
	v_mov_b32_e32 v63, v145
	v_mov_b32_e32 v62, v145
	v_mov_b32_e32 v61, v145
	v_mov_b32_e32 v60, v145
	v_mov_b32_e32 v59, v145
	v_mov_b32_e32 v58, v145
	v_mov_b32_e32 v49, v145
	v_mov_b32_e32 v48, v145
	v_mov_b32_e32 v47, v145
	v_mov_b32_e32 v46, v145
	v_mov_b32_e32 v45, v145
	v_mov_b32_e32 v44, v145
	v_mov_b32_e32 v43, v145
	v_mov_b32_e32 v42, v145
	v_mov_b32_e32 v33, v145
	v_mov_b32_e32 v32, v145
	v_mov_b32_e32 v31, v145
	v_mov_b32_e32 v30, v145
	v_mov_b32_e32 v29, v145
	v_mov_b32_e32 v28, v145
	v_mov_b32_e32 v27, v145
	v_mov_b32_e32 v26, v145
	v_mov_b32_e32 v17, v145
	v_mov_b32_e32 v16, v145
	v_mov_b32_e32 v15, v145
	v_mov_b32_e32 v14, v145
	v_mov_b32_e32 v13, v145
	v_mov_b32_e32 v12, v145
	v_mov_b32_e32 v11, v145
	v_mov_b32_e32 v10, v145
	v_mov_b32_e32 v57, v145
	v_mov_b32_e32 v56, v145
	v_mov_b32_e32 v55, v145
	v_mov_b32_e32 v54, v145
	v_mov_b32_e32 v53, v145
	v_mov_b32_e32 v52, v145
	v_mov_b32_e32 v51, v145
	v_mov_b32_e32 v50, v145
	v_mov_b32_e32 v41, v145
	v_mov_b32_e32 v40, v145
	v_mov_b32_e32 v39, v145
	v_mov_b32_e32 v38, v145
	v_mov_b32_e32 v37, v145
	v_mov_b32_e32 v36, v145
	v_mov_b32_e32 v35, v145
	v_mov_b32_e32 v34, v145
	v_mov_b32_e32 v25, v145
	v_mov_b32_e32 v24, v145
	v_mov_b32_e32 v23, v145
	v_mov_b32_e32 v22, v145
	v_mov_b32_e32 v21, v145
	v_mov_b32_e32 v20, v145
	v_mov_b32_e32 v19, v145
	v_mov_b32_e32 v18, v145
	v_mov_b32_e32 v9, v145
	v_mov_b32_e32 v8, v145
	v_mov_b32_e32 v7, v145
	v_mov_b32_e32 v6, v145
	v_mov_b32_e32 v5, v145
	v_mov_b32_e32 v4, v145
	v_mov_b32_e32 v3, v145
	v_mov_b32_e32 v2, v145
	s_branch .LBB0_41
.Lzskip_1:
	v_mov_b32_e32 v125, 0
	v_mov_b32_e32 v124, v125
	v_mov_b32_e32 v123, v125
	v_mov_b32_e32 v122, v125
	v_mov_b32_e32 v129, v125
	v_mov_b32_e32 v128, v125
	v_mov_b32_e32 v127, v125
	v_mov_b32_e32 v126, v125
	v_mov_b32_e32 v113, v125
	v_mov_b32_e32 v112, v125
	v_mov_b32_e32 v111, v125
	v_mov_b32_e32 v110, v125
	v_mov_b32_e32 v109, v125
	v_mov_b32_e32 v108, v125
	v_mov_b32_e32 v107, v125
	v_mov_b32_e32 v106, v125
	v_mov_b32_e32 v97, v125
	v_mov_b32_e32 v96, v125
	v_mov_b32_e32 v95, v125
	v_mov_b32_e32 v94, v125
	v_mov_b32_e32 v93, v125
	v_mov_b32_e32 v92, v125
	v_mov_b32_e32 v91, v125
	v_mov_b32_e32 v90, v125
	v_mov_b32_e32 v81, v125
	v_mov_b32_e32 v80, v125
	v_mov_b32_e32 v79, v125
	v_mov_b32_e32 v78, v125
	v_mov_b32_e32 v77, v125
	v_mov_b32_e32 v76, v125
	v_mov_b32_e32 v75, v125
	v_mov_b32_e32 v74, v125
	v_mov_b32_e32 v121, v125
	v_mov_b32_e32 v120, v125
	v_mov_b32_e32 v119, v125
	v_mov_b32_e32 v118, v125
	v_mov_b32_e32 v117, v125
	v_mov_b32_e32 v116, v125
	v_mov_b32_e32 v115, v125
	v_mov_b32_e32 v114, v125
	v_mov_b32_e32 v105, v125
	v_mov_b32_e32 v104, v125
	v_mov_b32_e32 v103, v125
	v_mov_b32_e32 v102, v125
	v_mov_b32_e32 v101, v125
	v_mov_b32_e32 v100, v125
	v_mov_b32_e32 v99, v125
	v_mov_b32_e32 v98, v125
	v_mov_b32_e32 v89, v125
	v_mov_b32_e32 v88, v125
	v_mov_b32_e32 v87, v125
	v_mov_b32_e32 v86, v125
	v_mov_b32_e32 v85, v125
	v_mov_b32_e32 v84, v125
	v_mov_b32_e32 v83, v125
	v_mov_b32_e32 v82, v125
	v_mov_b32_e32 v73, v125
	v_mov_b32_e32 v72, v125
	v_mov_b32_e32 v71, v125
	v_mov_b32_e32 v70, v125
	v_mov_b32_e32 v69, v125
	v_mov_b32_e32 v68, v125
	v_mov_b32_e32 v67, v125
	v_mov_b32_e32 v66, v125
	v_mov_b32_e32 v65, v125
	v_mov_b32_e32 v64, v125
	v_mov_b32_e32 v63, v125
	v_mov_b32_e32 v62, v125
	v_mov_b32_e32 v61, v125
	v_mov_b32_e32 v60, v125
	v_mov_b32_e32 v59, v125
	v_mov_b32_e32 v58, v125
	v_mov_b32_e32 v49, v125
	v_mov_b32_e32 v48, v125
	v_mov_b32_e32 v47, v125
	v_mov_b32_e32 v46, v125
	v_mov_b32_e32 v45, v125
	v_mov_b32_e32 v44, v125
	v_mov_b32_e32 v43, v125
	v_mov_b32_e32 v42, v125
	v_mov_b32_e32 v33, v125
	v_mov_b32_e32 v32, v125
	v_mov_b32_e32 v31, v125
	v_mov_b32_e32 v30, v125
	v_mov_b32_e32 v29, v125
	v_mov_b32_e32 v28, v125
	v_mov_b32_e32 v27, v125
	v_mov_b32_e32 v26, v125
	v_mov_b32_e32 v17, v125
	v_mov_b32_e32 v16, v125
	v_mov_b32_e32 v15, v125
	v_mov_b32_e32 v14, v125
	v_mov_b32_e32 v13, v125
	v_mov_b32_e32 v12, v125
	v_mov_b32_e32 v11, v125
	v_mov_b32_e32 v10, v125
	v_mov_b32_e32 v57, v125
	v_mov_b32_e32 v56, v125
	v_mov_b32_e32 v55, v125
	v_mov_b32_e32 v54, v125
	v_mov_b32_e32 v53, v125
	v_mov_b32_e32 v52, v125
	v_mov_b32_e32 v51, v125
	v_mov_b32_e32 v50, v125
	v_mov_b32_e32 v41, v125
	v_mov_b32_e32 v40, v125
	v_mov_b32_e32 v39, v125
	v_mov_b32_e32 v38, v125
	v_mov_b32_e32 v37, v125
	v_mov_b32_e32 v36, v125
	v_mov_b32_e32 v35, v125
	v_mov_b32_e32 v34, v125
	v_mov_b32_e32 v25, v125
	v_mov_b32_e32 v24, v125
	v_mov_b32_e32 v23, v125
	v_mov_b32_e32 v22, v125
	v_mov_b32_e32 v21, v125
	v_mov_b32_e32 v20, v125
	v_mov_b32_e32 v19, v125
	v_mov_b32_e32 v18, v125
	v_mov_b32_e32 v9, v125
	v_mov_b32_e32 v8, v125
	v_mov_b32_e32 v7, v125
	v_mov_b32_e32 v6, v125
	v_mov_b32_e32 v5, v125
	v_mov_b32_e32 v4, v125
	v_mov_b32_e32 v3, v125
	v_mov_b32_e32 v2, v125
	s_branch .LBB0_68
.Lzskip_2:
	v_mov_b32_e32 v129, 0
	v_mov_b32_e32 v128, v129
	v_mov_b32_e32 v127, v129
	v_mov_b32_e32 v126, v129
	v_mov_b32_e32 v125, v129
	v_mov_b32_e32 v124, v129
	v_mov_b32_e32 v123, v129
	v_mov_b32_e32 v122, v129
	v_mov_b32_e32 v113, v129
	v_mov_b32_e32 v112, v129
	v_mov_b32_e32 v111, v129
	v_mov_b32_e32 v110, v129
	v_mov_b32_e32 v109, v129
	v_mov_b32_e32 v108, v129
	v_mov_b32_e32 v107, v129
	v_mov_b32_e32 v106, v129
	v_mov_b32_e32 v97, v129
	v_mov_b32_e32 v96, v129
	v_mov_b32_e32 v95, v129
	v_mov_b32_e32 v94, v129
	v_mov_b32_e32 v93, v129
	v_mov_b32_e32 v92, v129
	v_mov_b32_e32 v91, v129
	v_mov_b32_e32 v90, v129
	v_mov_b32_e32 v81, v129
	v_mov_b32_e32 v80, v129
	v_mov_b32_e32 v79, v129
	v_mov_b32_e32 v78, v129
	v_mov_b32_e32 v77, v129
	v_mov_b32_e32 v76, v129
	v_mov_b32_e32 v75, v129
	v_mov_b32_e32 v74, v129
	v_mov_b32_e32 v121, v129
	v_mov_b32_e32 v120, v129
	v_mov_b32_e32 v119, v129
	v_mov_b32_e32 v118, v129
	v_mov_b32_e32 v117, v129
	v_mov_b32_e32 v116, v129
	v_mov_b32_e32 v115, v129
	v_mov_b32_e32 v114, v129
	v_mov_b32_e32 v105, v129
	v_mov_b32_e32 v104, v129
	v_mov_b32_e32 v103, v129
	v_mov_b32_e32 v102, v129
	v_mov_b32_e32 v101, v129
	v_mov_b32_e32 v100, v129
	v_mov_b32_e32 v99, v129
	v_mov_b32_e32 v98, v129
	v_mov_b32_e32 v89, v129
	v_mov_b32_e32 v88, v129
	v_mov_b32_e32 v87, v129
	v_mov_b32_e32 v86, v129
	v_mov_b32_e32 v85, v129
	v_mov_b32_e32 v84, v129
	v_mov_b32_e32 v83, v129
	v_mov_b32_e32 v82, v129
	v_mov_b32_e32 v73, v129
	v_mov_b32_e32 v72, v129
	v_mov_b32_e32 v71, v129
	v_mov_b32_e32 v70, v129
	v_mov_b32_e32 v69, v129
	v_mov_b32_e32 v68, v129
	v_mov_b32_e32 v67, v129
	v_mov_b32_e32 v66, v129
	v_mov_b32_e32 v65, v129
	v_mov_b32_e32 v64, v129
	v_mov_b32_e32 v63, v129
	v_mov_b32_e32 v62, v129
	v_mov_b32_e32 v61, v129
	v_mov_b32_e32 v60, v129
	v_mov_b32_e32 v59, v129
	v_mov_b32_e32 v58, v129
	v_mov_b32_e32 v49, v129
	v_mov_b32_e32 v48, v129
	v_mov_b32_e32 v47, v129
	v_mov_b32_e32 v46, v129
	v_mov_b32_e32 v45, v129
	v_mov_b32_e32 v44, v129
	v_mov_b32_e32 v43, v129
	v_mov_b32_e32 v42, v129
	v_mov_b32_e32 v33, v129
	v_mov_b32_e32 v32, v129
	v_mov_b32_e32 v31, v129
	v_mov_b32_e32 v30, v129
	v_mov_b32_e32 v29, v129
	v_mov_b32_e32 v28, v129
	v_mov_b32_e32 v27, v129
	v_mov_b32_e32 v26, v129
	v_mov_b32_e32 v17, v129
	v_mov_b32_e32 v16, v129
	v_mov_b32_e32 v15, v129
	v_mov_b32_e32 v14, v129
	v_mov_b32_e32 v13, v129
	v_mov_b32_e32 v12, v129
	v_mov_b32_e32 v11, v129
	v_mov_b32_e32 v10, v129
	v_mov_b32_e32 v57, v129
	v_mov_b32_e32 v56, v129
	v_mov_b32_e32 v55, v129
	v_mov_b32_e32 v54, v129
	v_mov_b32_e32 v53, v129
	v_mov_b32_e32 v52, v129
	v_mov_b32_e32 v51, v129
	v_mov_b32_e32 v50, v129
	v_mov_b32_e32 v41, v129
	v_mov_b32_e32 v40, v129
	v_mov_b32_e32 v39, v129
	v_mov_b32_e32 v38, v129
	v_mov_b32_e32 v37, v129
	v_mov_b32_e32 v36, v129
	v_mov_b32_e32 v35, v129
	v_mov_b32_e32 v34, v129
	v_mov_b32_e32 v25, v129
	v_mov_b32_e32 v24, v129
	v_mov_b32_e32 v23, v129
	v_mov_b32_e32 v22, v129
	v_mov_b32_e32 v21, v129
	v_mov_b32_e32 v20, v129
	v_mov_b32_e32 v19, v129
	v_mov_b32_e32 v18, v129
	v_mov_b32_e32 v9, v129
	v_mov_b32_e32 v8, v129
	v_mov_b32_e32 v7, v129
	v_mov_b32_e32 v6, v129
	v_mov_b32_e32 v5, v129
	v_mov_b32_e32 v4, v129
	v_mov_b32_e32 v3, v129
	v_mov_b32_e32 v2, v129
	s_branch .LBB0_103
.Lzskip_3:
	v_mov_b32_e32 v127, 0
	v_mov_b32_e32 v126, 0
	v_mov_b32_e32 v125, 0
	v_mov_b32_e32 v124, 0
	v_mov_b32_e32 v131, 0
	v_mov_b32_e32 v130, 0
	v_mov_b32_e32 v129, 0
	v_mov_b32_e32 v128, 0
	v_mov_b32_e32 v111, 0
	v_mov_b32_e32 v110, 0
	v_mov_b32_e32 v109, 0
	v_mov_b32_e32 v108, 0
	v_mov_b32_e32 v115, 0
	v_mov_b32_e32 v114, 0
	v_mov_b32_e32 v113, 0
	v_mov_b32_e32 v112, 0
	v_mov_b32_e32 v99, 0
	v_mov_b32_e32 v98, 0
	v_mov_b32_e32 v97, 0
	v_mov_b32_e32 v96, 0
	v_mov_b32_e32 v95, 0
	v_mov_b32_e32 v94, 0
	v_mov_b32_e32 v93, 0
	v_mov_b32_e32 v92, 0
	v_mov_b32_e32 v83, 0
	v_mov_b32_e32 v82, 0
	v_mov_b32_e32 v81, 0
	v_mov_b32_e32 v80, 0
	v_mov_b32_e32 v79, 0
	v_mov_b32_e32 v78, 0
	v_mov_b32_e32 v77, 0
	v_mov_b32_e32 v76, 0
	v_mov_b32_e32 v119, 0
	v_mov_b32_e32 v118, 0
	v_mov_b32_e32 v117, 0
	v_mov_b32_e32 v116, 0
	v_mov_b32_e32 v123, 0
	v_mov_b32_e32 v122, 0
	v_mov_b32_e32 v121, 0
	v_mov_b32_e32 v120, 0
	v_mov_b32_e32 v107, 0
	v_mov_b32_e32 v106, 0
	v_mov_b32_e32 v105, 0
	v_mov_b32_e32 v104, 0
	v_mov_b32_e32 v103, 0
	v_mov_b32_e32 v102, 0
	v_mov_b32_e32 v101, 0
	v_mov_b32_e32 v100, 0
	v_mov_b32_e32 v91, 0
	v_mov_b32_e32 v90, 0
	v_mov_b32_e32 v89, 0
	v_mov_b32_e32 v88, 0
	v_mov_b32_e32 v87, 0
	v_mov_b32_e32 v86, 0
	v_mov_b32_e32 v85, 0
	v_mov_b32_e32 v84, 0
	v_mov_b32_e32 v75, 0
	v_mov_b32_e32 v74, 0
	v_mov_b32_e32 v73, 0
	v_mov_b32_e32 v72, 0
	v_mov_b32_e32 v71, 0
	v_mov_b32_e32 v70, 0
	v_mov_b32_e32 v69, 0
	v_mov_b32_e32 v68, 0
	v_mov_b32_e32 v67, 0
	v_mov_b32_e32 v66, 0
	v_mov_b32_e32 v65, 0
	v_mov_b32_e32 v64, 0
	v_mov_b32_e32 v63, 0
	v_mov_b32_e32 v62, 0
	v_mov_b32_e32 v61, 0
	v_mov_b32_e32 v60, 0
	v_mov_b32_e32 v51, 0
	v_mov_b32_e32 v50, 0
	v_mov_b32_e32 v49, 0
	v_mov_b32_e32 v48, 0
	v_mov_b32_e32 v47, 0
	v_mov_b32_e32 v46, 0
	v_mov_b32_e32 v45, 0
	v_mov_b32_e32 v44, 0
	v_mov_b32_e32 v35, 0
	v_mov_b32_e32 v34, 0
	v_mov_b32_e32 v33, 0
	v_mov_b32_e32 v32, 0
	v_mov_b32_e32 v31, 0
	v_mov_b32_e32 v30, 0
	v_mov_b32_e32 v29, 0
	v_mov_b32_e32 v28, 0
	v_mov_b32_e32 v19, 0
	v_mov_b32_e32 v18, 0
	v_mov_b32_e32 v17, 0
	v_mov_b32_e32 v16, 0
	v_mov_b32_e32 v15, 0
	v_mov_b32_e32 v14, 0
	v_mov_b32_e32 v13, 0
	v_mov_b32_e32 v12, 0
	v_mov_b32_e32 v59, 0
	v_mov_b32_e32 v58, 0
	v_mov_b32_e32 v57, 0
	v_mov_b32_e32 v56, 0
	v_mov_b32_e32 v55, 0
	v_mov_b32_e32 v54, 0
	v_mov_b32_e32 v53, 0
	v_mov_b32_e32 v52, 0
	v_mov_b32_e32 v43, 0
	v_mov_b32_e32 v42, 0
	v_mov_b32_e32 v41, 0
	v_mov_b32_e32 v40, 0
	v_mov_b32_e32 v39, 0
	v_mov_b32_e32 v38, 0
	v_mov_b32_e32 v37, 0
	v_mov_b32_e32 v36, 0
	v_mov_b32_e32 v27, 0
	v_mov_b32_e32 v26, 0
	v_mov_b32_e32 v25, 0
	v_mov_b32_e32 v24, 0
	v_mov_b32_e32 v23, 0
	v_mov_b32_e32 v22, 0
	v_mov_b32_e32 v21, 0
	v_mov_b32_e32 v20, 0
	v_mov_b32_e32 v11, 0
	v_mov_b32_e32 v10, 0
	v_mov_b32_e32 v9, 0
	v_mov_b32_e32 v8, 0
	v_mov_b32_e32 v7, 0
	v_mov_b32_e32 v6, 0
	v_mov_b32_e32 v5, 0
	v_mov_b32_e32 v4, 0
	s_branch .LBB0_134
